# v048 stack + m1 fifth-round items remapped to blocks without a third step-3 GEMM tile (grid-size guarded)
# speedup vs baseline: 1.0089x; 1.0010x over previous
; __device__ void phase_m1(const P& p) {
;     ...
;   for (int it = BIDX; it < 16 * 68; it += gridDim.x) {
;     int bh = it / 68, blk = it % 68, b = bh >> 2, h = bh & 3;
.LBB0_444:
	s_or_b64 exec, exec, s[42:43]
	s_cmpk_lg_i32 s74, 0x100
	s_cbranch_scc1 .Lm1_generic
	s_cmpk_ge_i32 s4, 0x400
	s_cbranch_scc1 .LBB0_454
	s_add_i32 s4, s4, s74
	s_add_i32 s5, s5, s6
	s_sub_i32 s7, s7, s74
	s_cmpk_lt_i32 s4, 0x400
	s_cbranch_scc1 .LBB0_445
	s_and_b32 s2, s26, 7
	s_cmp_lt_u32 s2, 4
	s_cbranch_scc1 .LBB0_454
	s_cmp_ge_u32 s26, 128
	s_cbranch_scc1 .LBB0_454
	s_lshr_b32 s3, s26, 3
	s_lshl_b32 s3, s3, 2
	s_add_i32 s3, s3, s2
	s_add_i32 s4, s3, 0x3fc
	s_lshl_b32 s5, s4, 6
	s_sub_i32 s7, 0, s4
	s_branch .LBB0_445
.Lm1_generic:
	s_add_i32 s4, s4, s74
	s_add_i32 s5, s5, s6
	s_sub_i32 s7, s7, s74
	s_cmpk_lt_i32 s4, 0x440
	s_cbranch_scc0 .LBB0_454

; __device__ void phase_m2(const P& p) {
;     ...
;   const int per = 4096 + 32;
;   for (int idx = BIDX * NTHR + TIDX; idx < 32 * per; idx += gridDim.x * NTHR) {
.LBB0_506:
	s_andn2_b64 vcc, exec, s[0:1]
	s_cbranch_vccnz .LBB0_802
	v_readlane_b32 s0, v249, 56
	s_and_b32 s0, 0xffff, s0
	s_cmp_lg_u32 s0, 4
	s_cbranch_scc1 .LBB0_802
	v_mov_b32_e32 v0, v171
	s_mov_b32 s2, s26
	s_mov_b64 s[0:1], 0
	v_lshl_add_u32 v88, s2, 9, v0
	s_mov_b32 s2, 0x20400
	v_cmp_gt_i32_e32 vcc, s2, v88
	s_and_saveexec_b64 s[28:29], vcc
	s_cbranch_execz .LBB0_634
	s_add_u32 s0, s72, s0
	s_addc_u32 s1, s73, s1
	s_add_u32 s34, s0, 0x2aa3c000
	s_addc_u32 s35, s1, 0
	s_add_u32 s36, s0, 0x3323c000
	s_addc_u32 s37, s1, 0
	s_add_u32 s40, s0, 0x3334c000
	s_addc_u32 s41, s1, 0
	s_add_u32 s42, s0, 0x33350400
	s_addc_u32 s43, s1, 0
	s_add_u32 s44, s0, 0x37750400
	s_addc_u32 s45, s1, 0
	s_add_u32 s46, s0, 0x37860400
	s_addc_u32 s47, s1, 0
	s_mov_b64 s[48:49], 0
	s_mov_b32 s99, s95
	s_cmpk_lg_i32 s74, 0x100
	s_cbranch_scc1 .Lm2_inc_ok
	s_mov_b32 s99, 0x40000
	s_cmp_ge_u32 s26, 254
	s_cselect_b32 s99, 0x400, s99
.Lm2_inc_ok:
	s_branch .LBB0_512
.LBB0_510:
	s_or_b64 exec, exec, s[2:3]
